# m14 + grid barrier: L1 acquire invalidate issued at arrival (followers before the spin, XCD leader together with its release write-back) instead of after the spin
# speedup vs baseline: 1.0034x; 1.0034x over previous
; __device__ __forceinline__ unsigned xb_add(unsigned* p, unsigned v) { return __hip_atomic_fetch_add(p, v, __ATOMIC_RELAXED, __HIP_MEMORY_SCOPE_AGENT); }
; __device__ __forceinline__ void xcd_barrier(const XcdBarrier& b) {
;     ...
;         const unsigned old = xb_add(&bar[XB_XSUB(b.x)], 1u);
;         const unsigned gen = old / nloc;
;         if (old + 1u == (gen + 1u) * nloc) {
;             __builtin_amdgcn_fence(__ATOMIC_RELEASE, "agent");
;             asm volatile("s_waitcnt vmcnt(0)" ::: "memory");
;             const unsigned og = xb_add(&bar[XB_TOP], 1u);
.LBB11_194:
	s_andn2_saveexec_b64 s[10:11], s[10:11]
	s_cbranch_execz .LBB11_214
	s_mov_b64 s[10:11], exec
	buffer_wbl2 sc1
	buffer_inv sc1
	s_waitcnt lgkmcnt(0)
	s_waitcnt vmcnt(0)
	v_mbcnt_lo_u32_b32 v2, s10, 0
	v_mbcnt_hi_u32_b32 v2, s11, v2
	v_cmp_eq_u32_e32 vcc, 0, v2
	s_and_saveexec_b64 s[12:13], vcc
	s_cbranch_execz .LBB11_197
	s_bcnt1_i32_b64 s10, s[10:11]
	v_readlane_b32 s16, v249, 17
	v_mov_b32_e32 v3, 0x7000
	v_mov_b32_e32 v4, s10
	v_readlane_b32 s30, v249, 31
	v_readlane_b32 s31, v249, 32
	v_readlane_b32 s17, v249, 18
	v_readlane_b32 s18, v249, 19
	v_readlane_b32 s19, v249, 20
	v_readlane_b32 s20, v249, 21
	v_readlane_b32 s21, v249, 22
	global_atomic_add v3, v3, v4, s[30:31] offset:1024 sc0
	v_readlane_b32 s22, v249, 23
	v_readlane_b32 s23, v249, 24
	v_readlane_b32 s24, v249, 25
	v_readlane_b32 s25, v249, 26
	v_readlane_b32 s26, v249, 27
	v_readlane_b32 s27, v249, 28
	v_readlane_b32 s28, v249, 29
	v_readlane_b32 s29, v249, 30

; __device__ __forceinline__ unsigned xb_ld(unsigned* p)              { return __hip_atomic_load(p, __ATOMIC_RELAXED, __HIP_MEMORY_SCOPE_AGENT); }
; __device__ __forceinline__ unsigned xb_add(unsigned* p, unsigned v) { return __hip_atomic_fetch_add(p, v, __ATOMIC_RELAXED, __HIP_MEMORY_SCOPE_AGENT); }
; #define XB_SPIN(cond, bar) do { unsigned _sp = 0; while (cond) { __builtin_amdgcn_s_sleep(1); \
;     if ((++_sp & 255u) == 0u) { if (xb_ld(&(bar)[XB_TMO])) break; if (_sp > XB_SPIN_CAP) { atomicAdd(&(bar)[XB_TMO], 1u); break; } } } } while (0)
; __device__ __forceinline__ void xcd_barrier(const XcdBarrier& b) {
;     ...
;             const unsigned tg = og / nx;
;             if (og + 1u == (tg + 1u) * nx) xb_add(&bar[XB_TOPGEN], 1u);
;             else XB_SPIN(xb_ld(&bar[XB_TOPGEN]) == tg, bar);
;             __builtin_amdgcn_fence(__ATOMIC_ACQUIRE, "agent");
;             xb_add(&bar[XB_XGEN(b.x)], 1u);
;             asm volatile("s_waitcnt vmcnt(0)" ::: "memory");
.LBB11_211:
	s_or_b64 exec, exec, s[6:7]
	s_mov_b64 s[6:7], exec
	v_mbcnt_lo_u32_b32 v1, s6, 0
	v_mbcnt_hi_u32_b32 v1, s7, v1
	v_cmp_eq_u32_e32 vcc, 0, v1
	s_waitcnt vmcnt(0)
	s_and_saveexec_b64 s[10:11], vcc
	s_cbranch_execz .LBB11_213
	s_bcnt1_i32_b64 s6, s[6:7]
	v_mov_b32_e32 v1, 0
	v_mov_b32_e32 v2, s6
	global_atomic_add v1, v2, s[8:9]

; __device__ __forceinline__ unsigned xb_add(unsigned* p, unsigned v) { return __hip_atomic_fetch_add(p, v, __ATOMIC_RELAXED, __HIP_MEMORY_SCOPE_AGENT); }
; __device__ __forceinline__ void xcd_barrier(const XcdBarrier& b) {
;     ...
;         const unsigned old = xb_add(&bar[XB_XSUB(b.x)], 1u);
;         const unsigned gen = old / nloc;
;         if (old + 1u == (gen + 1u) * nloc) {
;             __builtin_amdgcn_fence(__ATOMIC_RELEASE, "agent");
;             asm volatile("s_waitcnt vmcnt(0)" ::: "memory");
;             const unsigned og = xb_add(&bar[XB_TOP], 1u);
.LBB11_409:
	s_andn2_saveexec_b64 s[6:7], s[6:7]
	s_cbranch_execz .LBB11_446
	s_mov_b64 s[6:7], exec
	buffer_wbl2 sc1
	buffer_inv sc1
	s_waitcnt lgkmcnt(0)
	s_waitcnt vmcnt(0)
	v_mbcnt_lo_u32_b32 v1, s6, 0
	v_mbcnt_hi_u32_b32 v1, s7, v1
	v_cmp_eq_u32_e32 vcc, 0, v1
	s_and_saveexec_b64 s[8:9], vcc
	s_cbranch_execz .LBB11_412
	s_bcnt1_i32_b64 s1, s[6:7]
	v_readlane_b32 s6, v250, 49
	v_mov_b32_e32 v4, s1
	v_readlane_b32 s7, v250, 50
	s_nop 4
	global_atomic_add v4, v3, v4, s[6:7] sc0

; __device__ __forceinline__ unsigned xb_ld(unsigned* p)              { return __hip_atomic_load(p, __ATOMIC_RELAXED, __HIP_MEMORY_SCOPE_AGENT); }
; __device__ __forceinline__ unsigned xb_add(unsigned* p, unsigned v) { return __hip_atomic_fetch_add(p, v, __ATOMIC_RELAXED, __HIP_MEMORY_SCOPE_AGENT); }
; #define XB_SPIN(cond, bar) do { unsigned _sp = 0; while (cond) { __builtin_amdgcn_s_sleep(1); \
;     if ((++_sp & 255u) == 0u) { if (xb_ld(&(bar)[XB_TMO])) break; if (_sp > XB_SPIN_CAP) { atomicAdd(&(bar)[XB_TMO], 1u); break; } } } } while (0)
; __device__ __forceinline__ void xcd_barrier(const XcdBarrier& b) {
;     ...
;             const unsigned tg = og / nx;
;             if (og + 1u == (tg + 1u) * nx) xb_add(&bar[XB_TOPGEN], 1u);
;             else XB_SPIN(xb_ld(&bar[XB_TOPGEN]) == tg, bar);
;             __builtin_amdgcn_fence(__ATOMIC_ACQUIRE, "agent");
;             xb_add(&bar[XB_XGEN(b.x)], 1u);
;             asm volatile("s_waitcnt vmcnt(0)" ::: "memory");
.LBB11_443:
	s_or_b64 exec, exec, s[6:7]
	s_mov_b64 s[6:7], exec
	v_mbcnt_lo_u32_b32 v1, s6, 0
	v_mbcnt_hi_u32_b32 v1, s7, v1
	v_cmp_eq_u32_e32 vcc, 0, v1
	s_waitcnt vmcnt(0)
	s_and_saveexec_b64 s[8:9], vcc
	s_cbranch_execz .LBB11_445
	s_bcnt1_i32_b64 s1, s[6:7]
	v_readlane_b32 s6, v250, 47
	v_mov_b32_e32 v1, s1
	v_readlane_b32 s7, v250, 48
	s_nop 4
	global_atomic_add v3, v1, s[6:7]

; __device__ __forceinline__ unsigned xb_add(unsigned* p, unsigned v) { return __hip_atomic_fetch_add(p, v, __ATOMIC_RELAXED, __HIP_MEMORY_SCOPE_AGENT); }
; __device__ __forceinline__ void xcd_barrier(const XcdBarrier& b) {
;     ...
;         const unsigned old = xb_add(&bar[XB_XSUB(b.x)], 1u);
;         const unsigned gen = old / nloc;
;         if (old + 1u == (gen + 1u) * nloc) {
;             __builtin_amdgcn_fence(__ATOMIC_RELEASE, "agent");
;             asm volatile("s_waitcnt vmcnt(0)" ::: "memory");
;             const unsigned og = xb_add(&bar[XB_TOP], 1u);
.LBB11_604:
	s_andn2_saveexec_b64 s[4:5], s[4:5]
	s_cbranch_execz .LBB11_624
	s_mov_b64 s[4:5], exec
	buffer_wbl2 sc1
	buffer_inv sc1
	s_waitcnt lgkmcnt(0)
	s_waitcnt vmcnt(0)
	v_mbcnt_lo_u32_b32 v1, s4, 0
	v_mbcnt_hi_u32_b32 v1, s5, v1
	v_cmp_eq_u32_e32 vcc, 0, v1
	s_and_saveexec_b64 s[8:9], vcc
	s_cbranch_execz .LBB11_607
	s_bcnt1_i32_b64 s1, s[4:5]
	v_readlane_b32 s4, v250, 49
	v_mov_b32_e32 v4, s1
	v_readlane_b32 s5, v250, 50
	s_nop 4
	global_atomic_add v4, v3, v4, s[4:5] sc0

; __device__ __forceinline__ unsigned xb_ld(unsigned* p)              { return __hip_atomic_load(p, __ATOMIC_RELAXED, __HIP_MEMORY_SCOPE_AGENT); }
; __device__ __forceinline__ unsigned xb_add(unsigned* p, unsigned v) { return __hip_atomic_fetch_add(p, v, __ATOMIC_RELAXED, __HIP_MEMORY_SCOPE_AGENT); }
; #define XB_SPIN(cond, bar) do { unsigned _sp = 0; while (cond) { __builtin_amdgcn_s_sleep(1); \
;     if ((++_sp & 255u) == 0u) { if (xb_ld(&(bar)[XB_TMO])) break; if (_sp > XB_SPIN_CAP) { atomicAdd(&(bar)[XB_TMO], 1u); break; } } } } while (0)
; __device__ __forceinline__ void xcd_barrier(const XcdBarrier& b) {
;     ...
;             const unsigned tg = og / nx;
;             if (og + 1u == (tg + 1u) * nx) xb_add(&bar[XB_TOPGEN], 1u);
;             else XB_SPIN(xb_ld(&bar[XB_TOPGEN]) == tg, bar);
;             __builtin_amdgcn_fence(__ATOMIC_ACQUIRE, "agent");
;             xb_add(&bar[XB_XGEN(b.x)], 1u);
;             asm volatile("s_waitcnt vmcnt(0)" ::: "memory");
.LBB11_621:
	s_or_b64 exec, exec, s[4:5]
	s_mov_b64 s[4:5], exec
	v_mbcnt_lo_u32_b32 v1, s4, 0
	v_mbcnt_hi_u32_b32 v1, s5, v1
	v_cmp_eq_u32_e32 vcc, 0, v1
	s_waitcnt vmcnt(0)
	s_and_saveexec_b64 s[8:9], vcc
	s_cbranch_execz .LBB11_623
	s_bcnt1_i32_b64 s1, s[4:5]
	v_readlane_b32 s4, v250, 47
	v_mov_b32_e32 v1, s1
	v_readlane_b32 s5, v250, 48
	s_nop 4
	global_atomic_add v3, v1, s[4:5]

; __device__ __forceinline__ unsigned xb_add(unsigned* p, unsigned v) { return __hip_atomic_fetch_add(p, v, __ATOMIC_RELAXED, __HIP_MEMORY_SCOPE_AGENT); }
; __device__ __forceinline__ void xcd_barrier(const XcdBarrier& b) {
;     ...
;         const unsigned old = xb_add(&bar[XB_XSUB(b.x)], 1u);
;         const unsigned gen = old / nloc;
;         if (old + 1u == (gen + 1u) * nloc) {
;             __builtin_amdgcn_fence(__ATOMIC_RELEASE, "agent");
;             asm volatile("s_waitcnt vmcnt(0)" ::: "memory");
;             const unsigned og = xb_add(&bar[XB_TOP], 1u);
.LBB11_883:
	s_andn2_saveexec_b64 s[4:5], s[4:5]
	s_cbranch_execz .LBB11_903
	s_mov_b64 s[4:5], exec
	buffer_wbl2 sc1
	buffer_inv sc1
	s_waitcnt lgkmcnt(0)
	s_waitcnt vmcnt(0)
	v_mbcnt_lo_u32_b32 v1, s4, 0
	v_mbcnt_hi_u32_b32 v1, s5, v1
	v_cmp_eq_u32_e32 vcc, 0, v1
	s_and_saveexec_b64 s[6:7], vcc
	s_cbranch_execz .LBB11_886
	s_bcnt1_i32_b64 s1, s[4:5]
	v_readlane_b32 s4, v250, 49
	v_mov_b32_e32 v4, s1
	v_readlane_b32 s5, v250, 50
	s_nop 4
	global_atomic_add v4, v3, v4, s[4:5] sc0

; __device__ __forceinline__ unsigned xb_ld(unsigned* p)              { return __hip_atomic_load(p, __ATOMIC_RELAXED, __HIP_MEMORY_SCOPE_AGENT); }
; __device__ __forceinline__ unsigned xb_add(unsigned* p, unsigned v) { return __hip_atomic_fetch_add(p, v, __ATOMIC_RELAXED, __HIP_MEMORY_SCOPE_AGENT); }
; #define XB_SPIN(cond, bar) do { unsigned _sp = 0; while (cond) { __builtin_amdgcn_s_sleep(1); \
;     if ((++_sp & 255u) == 0u) { if (xb_ld(&(bar)[XB_TMO])) break; if (_sp > XB_SPIN_CAP) { atomicAdd(&(bar)[XB_TMO], 1u); break; } } } } while (0)
; __device__ __forceinline__ void xcd_barrier(const XcdBarrier& b) {
;     ...
;             const unsigned tg = og / nx;
;             if (og + 1u == (tg + 1u) * nx) xb_add(&bar[XB_TOPGEN], 1u);
;             else XB_SPIN(xb_ld(&bar[XB_TOPGEN]) == tg, bar);
;             __builtin_amdgcn_fence(__ATOMIC_ACQUIRE, "agent");
;             xb_add(&bar[XB_XGEN(b.x)], 1u);
;             asm volatile("s_waitcnt vmcnt(0)" ::: "memory");
.LBB11_900:
	s_or_b64 exec, exec, s[4:5]
	s_mov_b64 s[4:5], exec
	v_mbcnt_lo_u32_b32 v1, s4, 0
	v_mbcnt_hi_u32_b32 v1, s5, v1
	v_cmp_eq_u32_e32 vcc, 0, v1
	s_waitcnt vmcnt(0)
	s_and_saveexec_b64 s[6:7], vcc
	s_cbranch_execz .LBB11_902
	s_bcnt1_i32_b64 s1, s[4:5]
	v_readlane_b32 s4, v250, 47
	v_mov_b32_e32 v1, s1
	v_readlane_b32 s5, v250, 48
	s_nop 4
	global_atomic_add v3, v1, s[4:5]

; __device__ __forceinline__ unsigned xb_add(unsigned* p, unsigned v) { return __hip_atomic_fetch_add(p, v, __ATOMIC_RELAXED, __HIP_MEMORY_SCOPE_AGENT); }
; __device__ __forceinline__ void xcd_barrier(const XcdBarrier& b) {
;     ...
;         const unsigned old = xb_add(&bar[XB_XSUB(b.x)], 1u);
;         const unsigned gen = old / nloc;
;         if (old + 1u == (gen + 1u) * nloc) {
;             __builtin_amdgcn_fence(__ATOMIC_RELEASE, "agent");
;             asm volatile("s_waitcnt vmcnt(0)" ::: "memory");
;             const unsigned og = xb_add(&bar[XB_TOP], 1u);
.LBB11_1702:
	s_andn2_saveexec_b64 s[4:5], s[4:5]
	s_cbranch_execz .LBB11_1722
	s_mov_b64 s[4:5], exec
	buffer_wbl2 sc1
	buffer_inv sc1
	s_waitcnt lgkmcnt(0)
	s_waitcnt vmcnt(0)
	v_mbcnt_lo_u32_b32 v1, s4, 0
	v_mbcnt_hi_u32_b32 v1, s5, v1
	v_cmp_eq_u32_e32 vcc, 0, v1
	s_and_saveexec_b64 s[14:15], vcc
	s_cbranch_execz .LBB11_1705
	s_bcnt1_i32_b64 s1, s[4:5]
	v_readlane_b32 s4, v250, 49
	v_mov_b32_e32 v4, s1
	v_readlane_b32 s5, v250, 50
	s_nop 4
	global_atomic_add v4, v3, v4, s[4:5] sc0

; __device__ __forceinline__ unsigned xb_ld(unsigned* p)              { return __hip_atomic_load(p, __ATOMIC_RELAXED, __HIP_MEMORY_SCOPE_AGENT); }
; __device__ __forceinline__ unsigned xb_add(unsigned* p, unsigned v) { return __hip_atomic_fetch_add(p, v, __ATOMIC_RELAXED, __HIP_MEMORY_SCOPE_AGENT); }
; #define XB_SPIN(cond, bar) do { unsigned _sp = 0; while (cond) { __builtin_amdgcn_s_sleep(1); \
;     if ((++_sp & 255u) == 0u) { if (xb_ld(&(bar)[XB_TMO])) break; if (_sp > XB_SPIN_CAP) { atomicAdd(&(bar)[XB_TMO], 1u); break; } } } } while (0)
; __device__ __forceinline__ void xcd_barrier(const XcdBarrier& b) {
;     ...
;             const unsigned tg = og / nx;
;             if (og + 1u == (tg + 1u) * nx) xb_add(&bar[XB_TOPGEN], 1u);
;             else XB_SPIN(xb_ld(&bar[XB_TOPGEN]) == tg, bar);
;             __builtin_amdgcn_fence(__ATOMIC_ACQUIRE, "agent");
;             xb_add(&bar[XB_XGEN(b.x)], 1u);
;             asm volatile("s_waitcnt vmcnt(0)" ::: "memory");
.LBB11_1719:
	s_or_b64 exec, exec, s[4:5]
	s_mov_b64 s[4:5], exec
	v_mbcnt_lo_u32_b32 v1, s4, 0
	v_mbcnt_hi_u32_b32 v1, s5, v1
	v_cmp_eq_u32_e32 vcc, 0, v1
	s_waitcnt vmcnt(0)
	s_and_saveexec_b64 s[14:15], vcc
	s_cbranch_execz .LBB11_1721
	s_bcnt1_i32_b64 s1, s[4:5]
	v_readlane_b32 s4, v250, 47
	v_mov_b32_e32 v1, s1
	v_readlane_b32 s5, v250, 48
	s_nop 4
	global_atomic_add v3, v1, s[4:5]
